# post-INIT grid sync routed through the two-level XCD barrier instance instead of the cooperative-groups software barrier
# speedup vs baseline: 1.0288x; 1.0002x over previous
; __global__ void __launch_bounds__(NTHR, 2) trunk_fwd(Params p) {
;     ...
;     if (threadIdx.x < 16) misc[threadIdx.x] = 0u;
;     __syncthreads();
;     XcdBarrier bar = xcd_barrier_post((unsigned*)(((const Params __attribute__((address_space(4)))*)__builtin_amdgcn_kernarg_segment_ptr())->ws + WS_CTL), misc);
;     do_phase<PH_INIT>(0, 0, lds);
;     grid.sync();
.LBB0_72:
	s_or_b64 exec, exec, s[14:15]
	v_lshrrev_b32_e32 v1, 20, v0
	v_lshrrev_b32_e32 v0, 10, v0
	v_or_b32_e32 v0, v0, v1
	s_movk_i32 s0, 0x3ff
	v_and_or_b32 v0, v0, s0, v162
	v_cmp_eq_u32_e32 vcc, 0, v0
	s_barrier
	s_and_saveexec_b64 s[0:1], vcc
	s_branch .LBB0_82
	buffer_wbl2 sc1
	s_waitcnt vmcnt(0)
	s_load_dwordx2 s[2:3], s[10:11], 0x58
	v_mov_b32_e32 v2, 0
	s_mov_b64 s[4:5], exec
	v_mbcnt_lo_u32_b32 v1, s4, 0
	v_mbcnt_hi_u32_b32 v1, s5, v1
	s_waitcnt lgkmcnt(0)
	global_load_dword v0, v2, s[2:3] offset:40
	v_cmp_eq_u32_e32 vcc, 0, v1
	s_and_saveexec_b64 s[10:11], vcc
	s_cbranch_execz .LBB0_75
	s_bcnt1_i32_b64 s4, s[4:5]
	v_mov_b32_e32 v3, s4
	global_atomic_add v3, v2, v3, s[2:3] offset:32 sc0

; __device__ __forceinline__ unsigned xb_ld(unsigned* p)              { return __hip_atomic_load(p, __ATOMIC_RELAXED, __HIP_MEMORY_SCOPE_AGENT); }
; __device__ __forceinline__ void xcd_barrier_complete(unsigned* bar, unsigned x, unsigned& nloc, unsigned& nx) {
;     const unsigned G = gridDim.x * gridDim.y * gridDim.z;
;     unsigned sum, cnt, mine, sp = 0u;
;     for (;;) {
;         sum = 0u; cnt = 0u; mine = 0u;
; #pragma unroll
;         for (unsigned j = 0; j < 16; ++j) { const unsigned c = xb_ld(&bar[XB_XCNT(j)]); sum += c; cnt += (c > 0u) ? 1u : 0u; mine = (j == x) ? c : mine; }
;         if (sum == G) break;
;         __builtin_amdgcn_s_sleep(1);
;         if ((++sp & 255u) == 0u) { if (xb_ld(&bar[XB_TMO])) break; if (sp > XB_SPIN_CAP) { atomicAdd(&bar[XB_TMO], 1u); break; } }
;     }
;     nloc = mine > 0u ? mine : 1u; nx = cnt > 0u ? cnt : 1u;
; }
; __global__ void __launch_bounds__(NTHR, 2) trunk_fwd(Params p) {
;     ...
;     XcdBarrier bar = xcd_barrier_post((unsigned*)(((const Params __attribute__((address_space(4)))*)__builtin_amdgcn_kernarg_segment_ptr())->ws + WS_CTL), misc);
;     do_phase<PH_INIT>(0, 0, lds);
;     grid.sync();
;     if (PROBE_MASK & 1) { do_phase<PH_INIT>(0, 0, lds); xcd_barrier(bar); }
;     ...
;     for (int hl = 0; hl < 8; ++hl) {
.LBB0_82:
	s_or_b64 exec, exec, s[0:1]
	s_mul_i32 s1, s71, s70
	s_ashr_i32 s71, s70, 31
	s_add_u32 s78, s6, 0x1d100200
	s_addc_u32 s79, s7, 0
	s_add_u32 s82, s6, 0x1d100400
	s_addc_u32 s83, s7, 0
	s_add_u32 s84, s6, 0x1d100500
	s_addc_u32 s85, s7, 0
	s_add_u32 s86, s6, 0x1d100600
	s_addc_u32 s87, s7, 0
	s_add_u32 s90, s6, 0x1d100700
	s_addc_u32 s91, s7, 0
	s_add_u32 s92, s6, 0x1d100800
	s_addc_u32 s93, s7, 0
	s_add_u32 s96, s6, 0x1d100900
	s_addc_u32 s97, s7, 0
	s_add_u32 s44, s6, 0x1d100a00
	s_addc_u32 s45, s7, 0
	s_add_u32 s46, s6, 0x1d100b00
	s_addc_u32 s47, s7, 0
	s_add_u32 s48, s6, 0x1d100c00
	s_addc_u32 s49, s7, 0
	s_add_u32 s50, s6, 0x1d100d00
	s_addc_u32 s51, s7, 0
	s_add_u32 s52, s6, 0x1d100e00
	s_addc_u32 s53, s7, 0
	s_add_u32 s36, s6, 0x1d100f00
	s_addc_u32 s37, s7, 0
	s_add_u32 s26, s6, 0x1d101000
	s_addc_u32 s27, s7, 0
	s_add_u32 s28, s6, 0x1d101100
	s_addc_u32 s29, s7, 0
	s_barrier
	s_load_dword s0, s[68:69], 0xe0
	s_add_u32 s30, s6, 0x1d101200
	s_addc_u32 s31, s7, 0
	s_add_u32 s56, s6, 0x1d101300
	s_addc_u32 s57, s7, 0
	s_cmp_eq_u32 s33, 15
	s_waitcnt lgkmcnt(0)
	s_mul_i32 s77, s1, s0
	s_cselect_b64 s[0:1], -1, 0
	s_cmp_eq_u32 s33, 14
	v_writelane_b32 v240, s0, 0
	v_mov_b32_e32 v164, 0x358637bd
	s_mov_b32 s35, 0x800000
	v_writelane_b32 v240, s1, 1
	s_cselect_b64 s[0:1], -1, 0
	v_writelane_b32 v240, s0, 2
	s_cmp_eq_u32 s33, 13
	v_mov_b32_e32 v1, 0
	v_writelane_b32 v240, s1, 3
	s_cselect_b64 s[0:1], -1, 0
	v_writelane_b32 v240, s0, 4
	s_cmp_eq_u32 s33, 12
	v_mov_b32_e32 v165, 1
	v_writelane_b32 v240, s1, 5
	s_cselect_b64 s[0:1], -1, 0
	v_writelane_b32 v240, s0, 6
	s_cmp_eq_u32 s33, 11
	v_mov_b32_e32 v166, 0x3ecc95a3
	v_writelane_b32 v240, s1, 7
	s_cselect_b64 s[0:1], -1, 0
	v_writelane_b32 v240, s0, 8
	s_cmp_eq_u32 s33, 10
	v_mov_b32_e32 v167, 0x3a27c5ac
	v_writelane_b32 v240, s1, 9
	s_cselect_b64 s[0:1], -1, 0
	v_writelane_b32 v240, s0, 10
	s_cmp_eq_u32 s33, 9
	v_mov_b32_e32 v168, 0xff800000
	v_writelane_b32 v240, s1, 11
	s_cselect_b64 s[0:1], -1, 0
	v_writelane_b32 v240, s0, 12
	s_cmp_eq_u32 s33, 8
	v_mov_b32_e32 v169, 0x42800000
	v_writelane_b32 v240, s1, 13
	s_cselect_b64 s[0:1], -1, 0
	v_writelane_b32 v240, s0, 14
	s_cmp_eq_u32 s33, 7
	v_mov_b32_e32 v146, 0x3f317218
	v_writelane_b32 v240, s1, 15
	s_cselect_b64 s[0:1], -1, 0
	v_writelane_b32 v240, s0, 16
	s_cmp_eq_u32 s33, 6
	v_mov_b32_e32 v170, 0x7fc00000
	v_writelane_b32 v240, s1, 17
	s_cselect_b64 s[0:1], -1, 0
	v_writelane_b32 v240, s0, 18
	s_cmp_eq_u32 s33, 5
	v_mov_b32_e32 v171, 0x3c00
	v_writelane_b32 v240, s1, 19
	s_cselect_b64 s[0:1], -1, 0
	v_writelane_b32 v240, s0, 20
	s_cmp_eq_u32 s33, 4
	v_not_b32_e32 v172, 63
	v_writelane_b32 v240, s1, 21
	s_cselect_b64 s[0:1], -1, 0
	v_writelane_b32 v240, s0, 22
	s_cmp_eq_u32 s33, 3
	v_mov_b32_e32 v173, 0x7f800000
	v_writelane_b32 v240, s1, 23
	s_cselect_b64 s[0:1], -1, 0
	v_writelane_b32 v240, s0, 24
	s_cmp_eq_u32 s33, 2
	s_mov_b32 s42, 0x10000
	v_writelane_b32 v240, s1, 25
	s_cselect_b64 s[0:1], -1, 0
	v_writelane_b32 v240, s0, 26
	s_cmp_eq_u32 s33, 1
	s_mov_b32 s43, 0x14000
	v_writelane_b32 v240, s1, 27
	s_cselect_b64 s[0:1], -1, 0
	v_writelane_b32 v240, s0, 28
	s_cmp_eq_u32 s33, 0
	s_mov_b32 s66, 0x1c000
	v_writelane_b32 v240, s1, 29
	s_cselect_b64 s[0:1], -1, 0
	v_writelane_b32 v240, s0, 30
	s_mov_b32 s63, 0xc000
	s_movk_i32 s64, 0x90
	v_writelane_b32 v240, s1, 31
	s_lshl_b32 s0, s33, 8
	s_add_u32 s0, s8, s0
	s_addc_u32 s1, s9, 0
	s_add_u32 s2, s0, 0x1400
	s_addc_u32 s3, s1, 0
	v_writelane_b32 v240, s2, 32
	s_add_u32 s0, s0, 0x2400
	s_addc_u32 s1, s1, 0
	v_writelane_b32 v240, s3, 33
	v_writelane_b32 v240, s0, 34
	s_movk_i32 s88, 0x110
	s_movk_i32 s65, 0x1e00
	v_writelane_b32 v240, s1, 35
	s_add_u32 s0, s6, 0x1d103400
	s_addc_u32 s1, s7, 0
	v_writelane_b32 v240, s0, 36
	s_mov_b64 s[14:15], 0
	s_mov_b64 s[80:81], 0x80
	v_writelane_b32 v240, s1, 37
	s_add_u32 s0, s6, 0x1d103500
	s_addc_u32 s1, s7, 0
	v_writelane_b32 v240, s0, 38
	s_ashr_i32 s75, s74, 31
	s_add_i32 s33, 0, 0x1c800
	v_writelane_b32 v240, s1, 39
	s_lshl_b32 s0, s70, 7
	v_writelane_b32 v240, s0, 40
	s_lshl_b32 s0, s70, 2
	v_writelane_b32 v240, s0, 41
	s_add_i32 s0, 0, 0x20100
	v_writelane_b32 v240, s0, 42
	s_add_i32 s0, 0, 0x20040
	v_writelane_b32 v240, s0, 43
	s_add_i32 s0, 0, 0x20044
	v_writelane_b32 v240, s0, 44
	s_add_i32 s0, 0, 0x16800
	v_writelane_b32 v240, s0, 45
	s_add_i32 s0, 0, 0x16200
	v_writelane_b32 v240, s0, 46
	s_add_i32 s0, 0, 0x17400
	v_writelane_b32 v240, s0, 47
	s_add_i32 s0, 0, 0x5100
	v_writelane_b32 v240, s0, 48
	s_add_i32 s0, 0, 0x1a800
	v_writelane_b32 v240, s0, 49
	s_add_i32 s0, 0, 0x13c00
	v_writelane_b32 v240, s0, 50
	s_lshl_b64 s[0:1], s[74:75], 12
	v_writelane_b32 v240, s0, 51
	s_mov_b32 s89, 0
	s_nop 0
	v_writelane_b32 v240, s1, 52
	s_lshl_b64 s[0:1], s[74:75], 11
	v_writelane_b32 v240, s0, 53
	s_nop 1
	v_writelane_b32 v240, s1, 54
	v_writelane_b32 v240, s67, 55
	v_writelane_b32 v240, s68, 56
	s_mov_b32 s0, s70
	s_nop 0
	v_writelane_b32 v240, s69, 57
	v_writelane_b32 v240, s0, 58
	s_nop 1
	v_writelane_b32 v240, s1, 59
	v_writelane_b32 v240, s72, 60
	s_mov_b32 s0, s74
	s_nop 0
	v_writelane_b32 v240, s73, 61
	v_writelane_b32 v240, s0, 62
	s_nop 1
	v_writelane_b32 v240, s1, 63
	s_mov_b32 s0, s76
	v_writelane_b32 v239, s0, 0
	s_nop 1
	v_writelane_b32 v239, s1, 1
	v_writelane_b32 v239, s71, 2
	v_writelane_b32 v239, s77, 3
	v_writelane_b32 v239, s78, 4
	s_nop 1
	v_writelane_b32 v239, s79, 5
	v_writelane_b32 v239, s82, 6
	s_nop 1
	v_writelane_b32 v239, s83, 7
	v_writelane_b32 v239, s84, 8
	s_nop 1
	v_writelane_b32 v239, s85, 9
	v_writelane_b32 v239, s86, 10
	s_nop 1
	v_writelane_b32 v239, s87, 11
	v_writelane_b32 v239, s90, 12
	s_nop 1
	v_writelane_b32 v239, s91, 13
	v_writelane_b32 v239, s92, 14
	s_nop 1
	v_writelane_b32 v239, s93, 15
	v_writelane_b32 v239, s96, 16
	s_nop 1
	v_writelane_b32 v239, s97, 17
	v_writelane_b32 v239, s44, 18
	s_nop 1
	v_writelane_b32 v239, s45, 19
	v_writelane_b32 v239, s46, 20
	s_nop 1
	v_writelane_b32 v239, s47, 21
	v_writelane_b32 v239, s48, 22
	s_nop 1
	v_writelane_b32 v239, s49, 23
	v_writelane_b32 v239, s50, 24
	s_nop 1
	v_writelane_b32 v239, s51, 25
	v_writelane_b32 v239, s52, 26
	s_nop 1
	v_writelane_b32 v239, s53, 27
	v_writelane_b32 v239, s36, 28
	s_nop 1
	v_writelane_b32 v239, s37, 29
	v_writelane_b32 v239, s26, 30
	s_nop 1
	v_writelane_b32 v239, s27, 31
	v_writelane_b32 v239, s28, 32
	s_nop 1
	v_writelane_b32 v239, s29, 33
	v_writelane_b32 v239, s30, 34
	s_nop 1
	v_writelane_b32 v239, s31, 35
	v_writelane_b32 v239, s56, 36
	s_nop 1
	v_writelane_b32 v239, s57, 37
	s_mov_b32 s99, 1
	s_branch .LBB0_114

; __device__ __forceinline__ unsigned xb_ld(unsigned* p)              { return __hip_atomic_load(p, __ATOMIC_RELAXED, __HIP_MEMORY_SCOPE_AGENT); }
; __device__ __forceinline__ unsigned xb_add(unsigned* p, unsigned v) { return __hip_atomic_fetch_add(p, v, __ATOMIC_RELAXED, __HIP_MEMORY_SCOPE_AGENT); }
; #define XB_SPIN(cond, bar) do { unsigned _sp = 0; while (cond) { __builtin_amdgcn_s_sleep(1); \
;     if ((++_sp & 255u) == 0u) { if (xb_ld(&(bar)[XB_TMO])) break; if (_sp > XB_SPIN_CAP) { atomicAdd(&(bar)[XB_TMO], 1u); break; } } } } while (0)
; #define RUN(PH) do { if (PROBE_MASK & (1 << PH)) { do_phase<PH, false>(layer, part, lds); GSYNC(); } do_phase<PH>(layer, part, lds); GSYNC(); } while (0)
; __device__ __forceinline__ void xcd_barrier(const XcdBarrier& b) {
;     asm volatile("s_waitcnt vmcnt(0)" ::: "memory");
;     __syncthreads();
;     if (threadIdx.x == 0) {
;         unsigned* bar = b.bar;
;         __builtin_amdgcn_s_waitcnt(0);
;         unsigned nloc = b.st[0], nx = b.st[1];
;         if (nloc == 0u) { xcd_barrier_complete(bar, b.x, nloc, nx); b.st[0] = nloc; b.st[1] = nx; }
;         const unsigned old = xb_add(&bar[XB_XSUB(b.x)], 1u);
;         const unsigned gen = old / nloc;
;         if (old + 1u == (gen + 1u) * nloc) {
;             __builtin_amdgcn_fence(__ATOMIC_RELEASE, "agent");
;             asm volatile("s_waitcnt vmcnt(0)" ::: "memory");
;             const unsigned og = xb_add(&bar[XB_TOP], 1u);
;             const unsigned tg = og / nx;
;             if (og + 1u == (tg + 1u) * nx) xb_add(&bar[XB_TOPGEN], 1u);
;             else XB_SPIN(xb_ld(&bar[XB_TOPGEN]) == tg, bar);
;             __builtin_amdgcn_fence(__ATOMIC_ACQUIRE, "agent");
;             xb_add(&bar[XB_XGEN(b.x)], 1u);
;             asm volatile("s_waitcnt vmcnt(0)" ::: "memory");
;         } else {
;             XB_SPIN(xb_ld(&bar[XB_XGEN(b.x)]) == gen, bar);
;             __builtin_amdgcn_fence(__ATOMIC_ACQUIRE, "agent");
;             asm volatile("s_waitcnt vmcnt(0)" ::: "memory");
;         }
;     }
;     __syncthreads();
; __global__ void __launch_bounds__(NTHR, 2) trunk_fwd(Params p) {
;     ...
;     for (int hl = 0; hl < 8; ++hl) {
;         const int layer = hl >> 1, part = hl & 1;
;         if (part == 0) {
;             RUN(PH_INPROJ);
.LBB0_166:
	s_or_b64 exec, exec, s[0:1]
	s_lshr_b32 s9, s14, 2
	s_mov_b64 s[0:1], 0
	s_waitcnt lgkmcnt(0)
	s_barrier
	s_cmp_eq_u32 s99, 1
	s_cbranch_scc0 .Lxb_normal
	s_mov_b32 s99, 0
	s_mov_b64 s[14:15], 0
	s_branch .LBB0_85
.Lxb_normal:
.LBB0_167:
	s_and_b64 vcc, exec, s[0:1]
	s_mov_b32 s25, s89
	s_cbranch_vccz .LBB0_715
	s_lshr_b32 s8, s14, 2
	s_and_b32 s2, s14, 2
	s_cmp_eq_u32 s2, 0
	v_writelane_b32 v239, s23, 40
	s_cselect_b64 s[14:15], -1, 0
	s_cmp_lg_u32 s2, 0
	v_writelane_b32 v239, s10, 41
	s_mov_b64 s[0:1], s[68:69]
	s_cselect_b64 s[4:5], -1, 0
	s_mov_b64 s[6:7], 0
	s_and_b64 vcc, exec, s[14:15]
	v_writelane_b32 v239, s11, 42
	s_cbranch_vccnz .LBB0_170
	s_load_dwordx2 s[2:3], s[0:1], 0x90
	s_mul_i32 s24, s8, 0x600
	s_lshl_b64 s[6:7], s[24:25], 2
	s_waitcnt lgkmcnt(0)
	s_add_u32 s6, s2, s6
	s_addc_u32 s7, s3, s7

; #define LAS __attribute__((address_space(3)))
; __global__ void __launch_bounds__(NTHR, 2) trunk_fwd(Params p) {
;     extern __shared__ __attribute__((aligned(16))) unsigned char lds[];
;     cg::grid_group grid = cg::this_grid();
;     volatile LAS unsigned* misc = (volatile LAS unsigned*)((LAS unsigned char*)lds + MISC_OFF);
;     if (threadIdx.x < 16) misc[threadIdx.x] = 0u;
;     __syncthreads();
;     XcdBarrier bar = xcd_barrier_post((unsigned*)(((const Params __attribute__((address_space(4)))*)__builtin_amdgcn_kernarg_segment_ptr())->ws + WS_CTL), misc);
	.amdhsa_kernel _Z9trunk_fwd6Params
		.amdhsa_group_segment_fixed_size 0
		.amdhsa_private_segment_fixed_size 0
		.amdhsa_kernarg_size 472
		.amdhsa_user_sgpr_count 2
		.amdhsa_user_sgpr_dispatch_ptr 0
		.amdhsa_user_sgpr_queue_ptr 0
		.amdhsa_user_sgpr_kernarg_segment_ptr 1
		.amdhsa_user_sgpr_dispatch_id 0
		.amdhsa_user_sgpr_kernarg_preload_length 0
		.amdhsa_user_sgpr_kernarg_preload_offset 0
		.amdhsa_user_sgpr_private_segment_size 0
		.amdhsa_uses_dynamic_stack 0
		.amdhsa_enable_private_segment 0
		.amdhsa_system_sgpr_workgroup_id_x 1
		.amdhsa_system_sgpr_workgroup_id_y 0
		.amdhsa_system_sgpr_workgroup_id_z 0
		.amdhsa_system_sgpr_workgroup_info 0
		.amdhsa_system_vgpr_workitem_id 2
		.amdhsa_next_free_vgpr 241
		.amdhsa_next_free_sgpr 102
		.amdhsa_accum_offset 244
		.amdhsa_reserve_vcc 1
		.amdhsa_float_round_mode_32 0
		.amdhsa_float_round_mode_16_64 0
		.amdhsa_float_denorm_mode_32 3
		.amdhsa_float_denorm_mode_16_64 3
		.amdhsa_dx10_clamp 1
		.amdhsa_ieee_mode 1
		.amdhsa_fp16_overflow 0
		.amdhsa_tg_split 0
		.amdhsa_exception_fp_ieee_invalid_op 0
		.amdhsa_exception_fp_denorm_src 0
		.amdhsa_exception_fp_ieee_div_zero 0
		.amdhsa_exception_fp_ieee_overflow 0
		.amdhsa_exception_fp_ieee_underflow 0
		.amdhsa_exception_fp_ieee_inexact 0
		.amdhsa_exception_int_div_zero 0
	.end_amdhsa_kernel

; #define LAS __attribute__((address_space(3)))
; __global__ void __launch_bounds__(NTHR, 2) trunk_fwd(Params p) {
;     extern __shared__ __attribute__((aligned(16))) unsigned char lds[];
;     cg::grid_group grid = cg::this_grid();
;     volatile LAS unsigned* misc = (volatile LAS unsigned*)((LAS unsigned char*)lds + MISC_OFF);
;     if (threadIdx.x < 16) misc[threadIdx.x] = 0u;
;     __syncthreads();
;     XcdBarrier bar = xcd_barrier_post((unsigned*)(((const Params __attribute__((address_space(4)))*)__builtin_amdgcn_kernarg_segment_ptr())->ws + WS_CTL), misc);
amdhsa.kernels:
  - .agpr_count:     0
    .args:
      - .offset:         0
        .size:           216
        .value_kind:     by_value
      - .offset:         216
        .size:           4
        .value_kind:     hidden_block_count_x
      - .offset:         220
        .size:           4
        .value_kind:     hidden_block_count_y
      - .offset:         224
        .size:           4
        .value_kind:     hidden_block_count_z
      - .offset:         228
        .size:           2
        .value_kind:     hidden_group_size_x
      - .offset:         230
        .size:           2
        .value_kind:     hidden_group_size_y
      - .offset:         232
        .size:           2
        .value_kind:     hidden_group_size_z
      - .offset:         234
        .size:           2
        .value_kind:     hidden_remainder_x
      - .offset:         236
        .size:           2
        .value_kind:     hidden_remainder_y
      - .offset:         238
        .size:           2
        .value_kind:     hidden_remainder_z
      - .offset:         256
        .size:           8
        .value_kind:     hidden_global_offset_x
      - .offset:         264
        .size:           8
        .value_kind:     hidden_global_offset_y
      - .offset:         272
        .size:           8
        .value_kind:     hidden_global_offset_z
      - .offset:         280
        .size:           2
        .value_kind:     hidden_grid_dims
      - .offset:         304
        .size:           8
        .value_kind:     hidden_multigrid_sync_arg
      - .offset:         336
        .size:           4
        .value_kind:     hidden_dynamic_lds_size
    .group_segment_fixed_size: 0
    .kernarg_segment_align: 8
    .kernarg_segment_size: 472
    .language:       OpenCL C
    .language_version:
      - 2
      - 0
    .max_flat_workgroup_size: 512
    .name:           _Z9trunk_fwd6Params
    .private_segment_fixed_size: 0
    .sgpr_count:     108
    .sgpr_spill_count: 305
    .symbol:         _Z9trunk_fwd6Params.kd
    .uniform_work_group_size: 1
    .uses_dynamic_stack: false
    .vgpr_count:     241
    .vgpr_spill_count: 0
    .wavefront_size: 64
